# packed f32 VALU ops in the conv/SiLU loop and indexer histogram pass split into scalar pairs (same per-lane operation)
# baseline (speedup 1.0000x reference)
; DI float bf2f(unsigned short u) { return __uint_as_float(((unsigned)u) << 16); }
; DI void phase_up(const Params& P, int layer, char* smem) {
;     ...
;       for (int r = 2 + rb; r < 128; r += 4) {
;         const int tb = tb0 + r;
;         if (tb < S_) {
;           const float val = bv + w0v * bf2f(Cs[(r - 2) * 136 + col]) + w1v * bf2f(Cs[(r - 1) * 136 + col]) + w2v * bf2f(Cs[r * 136 + col]);
;           const float gat = bgt + w0g * bf2f(Cs[(r - 2) * 136 + 64 + col]) + w1g * bf2f(Cs[(r - 1) * 136 + 64 + col]) + w2g * bf2f(Cs[r * 136 + 64 + col]);
;           const float a = gat / (1.f + __expf(-gat)) * val;
;           ACT[(size_t)(b * S_ + tb) * DFF + cv] = f2bf(a);
;         }
.LBB0_28:
	ds_read_u16_d16_hi v128, v10
	ds_read_u16_d16_hi v129, v10 offset:128
	ds_read_u16_d16_hi v130, v10 offset:272
	ds_read_u16_d16_hi v131, v10 offset:400
	ds_read_u16_d16_hi v132, v10 offset:544
	ds_read_u16_d16_hi v133, v10 offset:672
	ds_read_u16_d16_hi v134, v10 offset:816
	ds_read_u16_d16_hi v135, v10 offset:944
	s_waitcnt lgkmcnt(6)
	v_fma_f32 v118, v8, v128, v2
	v_fma_f32 v119, v9, v129, v3
	s_waitcnt lgkmcnt(4)
	v_fma_f32 v118, v6, v130, v118
	v_fma_f32 v119, v7, v131, v119
	v_fma_f32 v120, v8, v130, v2
	v_fma_f32 v121, v9, v131, v3
	s_waitcnt lgkmcnt(2)
	v_fma_f32 v118, v4, v132, v118
	v_fma_f32 v119, v5, v133, v119
	v_fma_f32 v120, v6, v132, v120
	v_fma_f32 v121, v7, v133, v121
	s_waitcnt lgkmcnt(0)
	v_mul_f32_e32 v12, 0xbfb8aa3b, v119
	v_fma_f32 v120, v4, v134, v120
	v_fma_f32 v121, v5, v135, v121
	v_exp_f32_e32 v12, v12
	s_nop 0
	v_mul_f32_e32 v18, 0xbfb8aa3b, v121
	v_add_f32_e32 v12, 1.0, v12
	v_exp_f32_e32 v18, v18
	v_div_scale_f32 v13, s[68:69], v12, v12, v119
	v_add_f32_e32 v18, 1.0, v18
	v_rcp_f32_e32 v14, v13
	v_div_scale_f32 v19, s[68:69], v18, v18, v121
	v_fma_f32 v15, -v13, v14, 1.0
	v_rcp_f32_e32 v122, v19
	v_fmac_f32_e32 v14, v15, v14
	v_div_scale_f32 v15, vcc, v119, v12, v119
	v_fma_f32 v123, -v19, v122, 1.0
	v_mul_f32_e32 v16, v15, v14
	v_fmac_f32_e32 v122, v123, v122
	v_fma_f32 v17, -v13, v16, v15
	v_fmac_f32_e32 v16, v17, v14
	v_fma_f32 v13, -v13, v16, v15
	v_div_fmas_f32 v13, v13, v14, v16
	v_div_scale_f32 v123, vcc, v121, v18, v121
	v_div_fixup_f32 v119, v13, v12, v119
	v_mul_f32_e32 v124, v123, v122
	v_mul_f32_e32 v118, v118, v119
	v_fma_f32 v125, -v19, v124, v123
	v_cvt_pk_bf16_f32 v12, v118, s0
	v_fmac_f32_e32 v124, v125, v122
	v_fma_f32 v19, -v19, v124, v123
	v_div_fmas_f32 v19, v19, v122, v124
	v_div_fixup_f32 v121, v19, v18, v121
	v_mul_f32_e32 v120, v120, v121
	v_cvt_pk_bf16_f32 v18, v120, s0
	s_add_i32 s23, s28, s22
	s_cmp_lt_i32 s23, s4
	s_cbranch_scc0 .Lconv_skipA
	global_store_short v126, v12, s[20:21]

; template <int MODE>
; DI void indexer_pass(const _Float16* kbase, int ntile_in, int ts, const f16x8 (&qf)[8][2], const f16x8 (&qc)[2], const float (&wq)[8], float* csc,
;                      unsigned short* cix, int* cnt, float* tau, unsigned* hist, int* oflow, int lane, int w) {
;     ...
;       int tl = NG * (st + 1) + g; tl = tl < ntile ? tl : ntile - 1;
;       nxt[g][0] = *(const f16x8*)(kbase + (size_t)(tl * ts) * 64 * ZLD);
;       nxt[g][1] = *(const f16x8*)(kbase + (size_t)(tl * ts) * 64 * ZLD + 32);
;     }
;     if (MODE == 2) tq = tau[q];
; #pragma unroll
;     for (int g = 0; g < NG; ++g) {
;       const int tl = NG * st + g;
;       if (tl < ntile) {
;         f32x4 lin = {0.f, 0.f, 0.f, 0.f};
;         lin = __builtin_amdgcn_mfma_f32_16x16x32_f16(cur[g][0], qc[0], lin, 0, 0, 0);
;         lin = __builtin_amdgcn_mfma_f32_16x16x32_f16(cur[g][1], qc[1], lin, 0, 0, 0);
;         float s[4] = {lin[0], lin[1], lin[2], lin[3]};
;         f32x4 accp = {0.f, 0.f, 0.f, 0.f};
;         accp = __builtin_amdgcn_mfma_f32_16x16x32_f16(cur[g][0], qf[0][0], accp, 0, 0, 0);
;         accp = __builtin_amdgcn_mfma_f32_16x16x32_f16(cur[g][1], qf[0][1], accp, 0, 0, 0);
; #pragma unroll
;         for (int h = 0; h < 8; ++h) {
;           f32x4 accn = {0.f, 0.f, 0.f, 0.f};
;           if (h < 7) {
;             accn = __builtin_amdgcn_mfma_f32_16x16x32_f16(cur[g][0], qf[h + 1][0], accn, 0, 0, 0);
;             accn = __builtin_amdgcn_mfma_f32_16x16x32_f16(cur[g][1], qf[h + 1][1], accn, 0, 0, 0);
;           }
;           __builtin_amdgcn_sched_barrier(0);
; #pragma unroll
;           for (int r = 0; r < 4; ++r) {
;             s[r] = fmaf(wq[h], __builtin_fabsf(accp[r]), s[r]);
;             asm("" : "+v"(s[r]));
;           }
;           __builtin_amdgcn_sched_barrier(0);
;           accp = accn;
;         }
;         if (MODE == 0) {
; #pragma unroll
;           for (int r = 0; r < 4; ++r) {
;             const float score = s[r] + 0.f;
;             const unsigned bits = __float_as_uint(score);
;             int p = (int)((bits & 0x7fffffffu) >> 19) - (HB_LO - 1);
;             p = p < 0 ? 0 : (p > HB_P ? HB_P : p);
;             const int bin = (bits >> 31) ? (HB_P - p) : (HB_P + 1 + p);
;             atomicAdd(hist + q * HB_WORDS + bin, 1u);
;           }
.LBB0_273:
	s_add_i32 s0, s21, 1
	v_min_i32_e32 v72, s0, v235
	v_lshlrev_b32_e32 v72, v233, v72
	s_waitcnt vmcnt(14)
	v_mad_i64_i32 v[76:77], s[0:1], v72, s93, v[146:147]
	s_add_i32 s0, s21, 2
	s_waitcnt vmcnt(13)
	v_min_i32_e32 v80, s0, v235
	v_lshlrev_b32_e32 v80, v233, v80
	s_waitcnt vmcnt(12)
	v_mad_i64_i32 v[84:85], s[0:1], v80, s93, v[146:147]
	s_add_i32 s0, s21, 3
	s_add_i32 s20, s21, 4
	s_waitcnt vmcnt(11)
	v_min_i32_e32 v88, s0, v235
	s_waitcnt vmcnt(9)
	v_min_i32_e32 v96, s20, v235
	v_lshlrev_b32_e32 v88, v233, v88
	v_lshlrev_b32_e32 v96, v233, v96
	v_mad_i64_i32 v[92:93], s[0:1], v88, s93, v[146:147]
	s_waitcnt vmcnt(8)
	v_mad_i64_i32 v[100:101], s[0:1], v96, s93, v[146:147]
	global_load_dwordx4 v[72:75], v[76:77], off
	s_nop 0
	global_load_dwordx4 v[76:79], v[76:77], off offset:64
	s_nop 0
	global_load_dwordx4 v[80:83], v[84:85], off
	s_nop 0
	global_load_dwordx4 v[84:87], v[84:85], off offset:64
	s_nop 0
	global_load_dwordx4 v[88:91], v[92:93], off
	s_nop 0
	global_load_dwordx4 v[92:95], v[92:93], off offset:64
	s_nop 0
	global_load_dwordx4 v[96:99], v[100:101], off
	s_nop 0
	global_load_dwordx4 v[100:103], v[100:101], off offset:64
	s_add_i32 s0, s21, -3
	v_cmp_lt_i32_e64 s[0:1], s0, v234
	s_and_saveexec_b64 s[18:19], s[0:1]
	s_cbranch_execz .LBB0_275
	s_waitcnt vmcnt(8)
	v_mfma_f32_16x16x32_f16 v[242:245], v[132:135], v[64:67], 0
	v_mfma_f32_16x16x32_f16 v[246:249], v[132:135], v[0:3], 0
	v_mfma_f32_16x16x32_f16 v[238:241], v[132:135], v[8:11], 0
	v_mfma_f32_16x16x32_f16 v[242:245], v[128:131], v[68:71], v[242:245]
	v_mfma_f32_16x16x32_f16 v[246:249], v[128:131], v[4:7], v[246:249]
	v_mfma_f32_16x16x32_f16 v[238:241], v[128:131], v[12:15], v[238:241]
	s_nop 6
	v_fma_f32 v136, v162, |v246|, v242
	v_fma_f32 v237, v162, |v247|, v243
	v_fma_f32 v246, v162, |v248|, v244
	v_fma_f32 v247, v162, |v249|, v245
	v_mfma_f32_16x16x32_f16 v[242:245], v[132:135], v[16:19], 0
	v_mfma_f32_16x16x32_f16 v[242:245], v[128:131], v[20:23], v[242:245]
	v_fma_f32 v136, v164, |v238|, v136
	v_fma_f32 v237, v164, |v239|, v237
	v_fma_f32 v246, v164, |v240|, v246
	v_fma_f32 v247, v164, |v241|, v247
	v_mfma_f32_16x16x32_f16 v[238:241], v[132:135], v[24:27], 0
	v_mfma_f32_16x16x32_f16 v[238:241], v[128:131], v[28:31], v[238:241]
	s_nop 1
	v_fma_f32 v136, v166, |v242|, v136
	v_fma_f32 v237, v166, |v243|, v237
	v_fma_f32 v246, v166, |v244|, v246
	v_fma_f32 v247, v166, |v245|, v247
	v_mfma_f32_16x16x32_f16 v[242:245], v[132:135], v[32:35], 0
	v_mfma_f32_16x16x32_f16 v[242:245], v[128:131], v[36:39], v[242:245]
	v_fma_f32 v136, v168, |v238|, v136
	v_fma_f32 v237, v168, |v239|, v237
	v_fma_f32 v246, v168, |v240|, v246
	v_fma_f32 v247, v168, |v241|, v247
	v_mfma_f32_16x16x32_f16 v[238:241], v[132:135], v[40:43], 0
	v_mfma_f32_16x16x32_f16 v[238:241], v[128:131], v[44:47], v[238:241]
	s_nop 1
	v_fma_f32 v136, v170, |v242|, v136
	v_fma_f32 v237, v170, |v243|, v237
	v_fma_f32 v246, v170, |v244|, v246
	v_fma_f32 v247, v170, |v245|, v247
	v_mfma_f32_16x16x32_f16 v[242:245], v[132:135], v[48:51], 0
	v_mfma_f32_16x16x32_f16 v[242:245], v[128:131], v[52:55], v[242:245]
	v_fma_f32 v136, v172, |v238|, v136
	v_fma_f32 v237, v172, |v239|, v237
	v_fma_f32 v238, v172, |v240|, v246
	v_fma_f32 v239, v172, |v241|, v247
	v_mfma_f32_16x16x32_f16 v[132:135], v[132:135], v[56:59], 0
	v_mfma_f32_16x16x32_f16 v[128:131], v[128:131], v[60:63], v[132:135]
	s_nop 6
	v_fma_f32 v132, v174, |v242|, v136
	v_fma_f32 v134, v174, |v243|, v237
	v_fma_f32 v135, v174, |v244|, v238
	v_fma_f32 v136, v174, |v245|, v239
	s_nop 0
	v_fma_f32 v133, v176, |v128|, v132
	v_fma_f32 v132, v176, |v129|, v134
	v_fma_f32 v129, v176, |v130|, v135
	v_fma_f32 v128, v176, |v131|, v136
	s_nop 0
	v_add_f32_e32 v130, 0, v132
	v_add_f32_e32 v131, 0, v133
	v_add_f32_e32 v128, 0, v128
	v_add_f32_e32 v129, 0, v129
	v_bfe_u32 v132, v131, 19, 12
	v_med3_u32 v132, v132, s76, v203
	v_sub_u32_e32 v133, 0x87f, v132
	v_add_u32_e32 v132, 0xfffff902, v132
	v_cmp_gt_i32_e64 s[0:1], 0, v131
	s_nop 1
	v_cndmask_b32_e64 v131, v132, v133, s[0:1]
	v_lshl_add_u32 v131, v131, 2, v211
	ds_add_u32 v131, v175
	v_bfe_u32 v131, v130, 19, 12
	v_med3_u32 v131, v131, s76, v203
	v_sub_u32_e32 v132, 0x87f, v131
	v_add_u32_e32 v131, 0xfffff902, v131
	v_cmp_gt_i32_e64 s[0:1], 0, v130
	s_nop 1
	v_cndmask_b32_e64 v130, v131, v132, s[0:1]
	v_lshl_add_u32 v130, v130, 2, v211
	ds_add_u32 v130, v175
	v_bfe_u32 v130, v129, 19, 12
	v_med3_u32 v130, v130, s76, v203
	v_sub_u32_e32 v131, 0x87f, v130
	v_add_u32_e32 v130, 0xfffff902, v130
	v_cmp_gt_i32_e64 s[0:1], 0, v129
	s_nop 1
	v_cndmask_b32_e64 v129, v130, v131, s[0:1]
	v_lshl_add_u32 v129, v129, 2, v211
	ds_add_u32 v129, v175
	v_bfe_u32 v129, v128, 19, 12
	v_med3_u32 v129, v129, s76, v203
	v_sub_u32_e32 v130, 0x87f, v129
	v_add_u32_e32 v129, 0xfffff902, v129
	v_cmp_gt_i32_e64 s[0:1], 0, v128
	s_nop 1
	v_cndmask_b32_e64 v128, v129, v130, s[0:1]
	v_lshl_add_u32 v128, v128, 2, v211
	ds_add_u32 v128, v175
; template <int MODE>
; DI void indexer_pass(const _Float16* kbase, int ntile_in, int ts, const f16x8 (&qf)[8][2], const f16x8 (&qc)[2], const float (&wq)[8], float* csc,
;                      unsigned short* cix, int* cnt, float* tau, unsigned* hist, int* oflow, int lane, int w) {
;     ...
;     for (int g = 0; g < NG; ++g) {
;       const int tl = NG * st + g;
;       if (tl < ntile) {
;         f32x4 lin = {0.f, 0.f, 0.f, 0.f};
;         lin = __builtin_amdgcn_mfma_f32_16x16x32_f16(cur[g][0], qc[0], lin, 0, 0, 0);
;         lin = __builtin_amdgcn_mfma_f32_16x16x32_f16(cur[g][1], qc[1], lin, 0, 0, 0);
;         float s[4] = {lin[0], lin[1], lin[2], lin[3]};
;         f32x4 accp = {0.f, 0.f, 0.f, 0.f};
;         accp = __builtin_amdgcn_mfma_f32_16x16x32_f16(cur[g][0], qf[0][0], accp, 0, 0, 0);
;         accp = __builtin_amdgcn_mfma_f32_16x16x32_f16(cur[g][1], qf[0][1], accp, 0, 0, 0);
; #pragma unroll
;         for (int h = 0; h < 8; ++h) {
;           f32x4 accn = {0.f, 0.f, 0.f, 0.f};
;           if (h < 7) {
;             accn = __builtin_amdgcn_mfma_f32_16x16x32_f16(cur[g][0], qf[h + 1][0], accn, 0, 0, 0);
;             accn = __builtin_amdgcn_mfma_f32_16x16x32_f16(cur[g][1], qf[h + 1][1], accn, 0, 0, 0);
;           }
;           __builtin_amdgcn_sched_barrier(0);
; #pragma unroll
;           for (int r = 0; r < 4; ++r) {
;             s[r] = fmaf(wq[h], __builtin_fabsf(accp[r]), s[r]);
;             asm("" : "+v"(s[r]));
;           }
;           __builtin_amdgcn_sched_barrier(0);
;           accp = accn;
;         }
;         if (MODE == 0) {
; #pragma unroll
;           for (int r = 0; r < 4; ++r) {
;             const float score = s[r] + 0.f;
;             const unsigned bits = __float_as_uint(score);
;             int p = (int)((bits & 0x7fffffffu) >> 19) - (HB_LO - 1);
;             p = p < 0 ? 0 : (p > HB_P ? HB_P : p);
;             const int bin = (bits >> 31) ? (HB_P - p) : (HB_P + 1 + p);
;             atomicAdd(hist + q * HB_WORDS + bin, 1u);
;           }
.LBB0_275:
	s_or_b64 exec, exec, s[18:19]
	s_add_i32 s0, s21, -2
	v_cmp_lt_i32_e64 s[0:1], s0, v234
	s_and_saveexec_b64 s[18:19], s[0:1]
	s_cbranch_execz .LBB0_277
	s_waitcnt vmcnt(9)
	v_mfma_f32_16x16x32_f16 v[128:131], v[124:127], v[64:67], 0
	s_waitcnt vmcnt(8)
	v_mfma_f32_16x16x32_f16 v[132:135], v[124:127], v[0:3], 0
	v_mfma_f32_16x16x32_f16 v[238:241], v[124:127], v[8:11], 0
	v_mfma_f32_16x16x32_f16 v[128:131], v[120:123], v[68:71], v[128:131]
	v_mfma_f32_16x16x32_f16 v[132:135], v[120:123], v[4:7], v[132:135]
	v_mfma_f32_16x16x32_f16 v[238:241], v[120:123], v[12:15], v[238:241]
	s_nop 6
	v_fma_f32 v132, v162, |v132|, v128
	v_fma_f32 v133, v162, |v133|, v129
	v_fma_f32 v134, v162, |v134|, v130
	v_fma_f32 v135, v162, |v135|, v131
	v_mfma_f32_16x16x32_f16 v[128:131], v[124:127], v[16:19], 0
	v_mfma_f32_16x16x32_f16 v[128:131], v[120:123], v[20:23], v[128:131]
	v_fma_f32 v136, v164, |v238|, v132
	v_fma_f32 v237, v164, |v239|, v133
	v_fma_f32 v238, v164, |v240|, v134
	v_fma_f32 v239, v164, |v241|, v135
	v_mfma_f32_16x16x32_f16 v[132:135], v[124:127], v[24:27], 0
	v_mfma_f32_16x16x32_f16 v[132:135], v[120:123], v[28:31], v[132:135]
	s_nop 1
	v_fma_f32 v136, v166, |v128|, v136
	v_fma_f32 v237, v166, |v129|, v237
	v_fma_f32 v238, v166, |v130|, v238
	v_fma_f32 v239, v166, |v131|, v239
	v_mfma_f32_16x16x32_f16 v[128:131], v[124:127], v[32:35], 0
	v_mfma_f32_16x16x32_f16 v[128:131], v[120:123], v[36:39], v[128:131]
	v_fma_f32 v136, v168, |v132|, v136
	v_fma_f32 v237, v168, |v133|, v237
	v_fma_f32 v238, v168, |v134|, v238
	v_fma_f32 v239, v168, |v135|, v239
	v_mfma_f32_16x16x32_f16 v[132:135], v[124:127], v[40:43], 0
	v_mfma_f32_16x16x32_f16 v[132:135], v[120:123], v[44:47], v[132:135]
	s_nop 1
	v_fma_f32 v136, v170, |v128|, v136
	v_fma_f32 v237, v170, |v129|, v237
	v_fma_f32 v238, v170, |v130|, v238
	v_fma_f32 v239, v170, |v131|, v239
	v_mfma_f32_16x16x32_f16 v[128:131], v[124:127], v[48:51], 0
	v_mfma_f32_16x16x32_f16 v[128:131], v[120:123], v[52:55], v[128:131]
	v_fma_f32 v132, v172, |v132|, v136
	v_fma_f32 v133, v172, |v133|, v237
	v_fma_f32 v134, v172, |v134|, v238
	v_fma_f32 v135, v172, |v135|, v239
	v_mfma_f32_16x16x32_f16 v[124:127], v[124:127], v[56:59], 0
	v_mfma_f32_16x16x32_f16 v[120:123], v[120:123], v[60:63], v[124:127]
	s_nop 6
	v_fma_f32 v124, v174, |v128|, v132
	v_fma_f32 v126, v174, |v129|, v133
	v_fma_f32 v127, v174, |v130|, v134
	v_fma_f32 v128, v174, |v131|, v135
	s_nop 0
	v_fma_f32 v125, v176, |v120|, v124
	v_fma_f32 v124, v176, |v121|, v126
	v_fma_f32 v121, v176, |v122|, v127
	v_fma_f32 v120, v176, |v123|, v128
	s_nop 0
	v_add_f32_e32 v122, 0, v124
	v_add_f32_e32 v123, 0, v125
	v_add_f32_e32 v120, 0, v120
	v_add_f32_e32 v121, 0, v121
	v_bfe_u32 v124, v123, 19, 12
	v_med3_u32 v124, v124, s76, v203
	v_sub_u32_e32 v125, 0x87f, v124
	v_add_u32_e32 v124, 0xfffff902, v124
	v_cmp_gt_i32_e64 s[0:1], 0, v123
	s_nop 1
	v_cndmask_b32_e64 v123, v124, v125, s[0:1]
	v_lshl_add_u32 v123, v123, 2, v211
	ds_add_u32 v123, v175
	v_bfe_u32 v123, v122, 19, 12
	v_med3_u32 v123, v123, s76, v203
	v_sub_u32_e32 v124, 0x87f, v123
	v_add_u32_e32 v123, 0xfffff902, v123
	v_cmp_gt_i32_e64 s[0:1], 0, v122
	s_nop 1
	v_cndmask_b32_e64 v122, v123, v124, s[0:1]
	v_lshl_add_u32 v122, v122, 2, v211
	ds_add_u32 v122, v175
	v_bfe_u32 v122, v121, 19, 12
	v_med3_u32 v122, v122, s76, v203
	v_sub_u32_e32 v123, 0x87f, v122
	v_add_u32_e32 v122, 0xfffff902, v122
	v_cmp_gt_i32_e64 s[0:1], 0, v121
	s_nop 1
	v_cndmask_b32_e64 v121, v122, v123, s[0:1]
	v_lshl_add_u32 v121, v121, 2, v211
	ds_add_u32 v121, v175
	v_bfe_u32 v121, v120, 19, 12
	v_med3_u32 v121, v121, s76, v203
	v_sub_u32_e32 v122, 0x87f, v121
	v_add_u32_e32 v121, 0xfffff902, v121
	v_cmp_gt_i32_e64 s[0:1], 0, v120
	s_nop 1
	v_cndmask_b32_e64 v120, v121, v122, s[0:1]
	v_lshl_add_u32 v120, v120, 2, v211
	ds_add_u32 v120, v175
.LBB0_277:
	s_or_b64 exec, exec, s[18:19]
	s_add_i32 s0, s21, -1
	v_cmp_lt_i32_e64 s[0:1], s0, v234
	s_and_saveexec_b64 s[18:19], s[0:1]
	s_cbranch_execz .LBB0_279
	s_waitcnt vmcnt(11)
	v_mfma_f32_16x16x32_f16 v[120:123], v[116:119], v[64:67], 0
	s_waitcnt vmcnt(10)
	v_mfma_f32_16x16x32_f16 v[124:127], v[116:119], v[0:3], 0
	s_waitcnt vmcnt(9)
	v_mfma_f32_16x16x32_f16 v[128:131], v[116:119], v[8:11], 0
	v_mfma_f32_16x16x32_f16 v[120:123], v[112:115], v[68:71], v[120:123]
	v_mfma_f32_16x16x32_f16 v[124:127], v[112:115], v[4:7], v[124:127]
	v_mfma_f32_16x16x32_f16 v[128:131], v[112:115], v[12:15], v[128:131]
	s_nop 6
	v_fma_f32 v124, v162, |v124|, v120
	v_fma_f32 v125, v162, |v125|, v121
	v_fma_f32 v126, v162, |v126|, v122
	v_fma_f32 v127, v162, |v127|, v123
	v_mfma_f32_16x16x32_f16 v[120:123], v[116:119], v[16:19], 0
	v_mfma_f32_16x16x32_f16 v[120:123], v[112:115], v[20:23], v[120:123]
	v_fma_f32 v128, v164, |v128|, v124
	v_fma_f32 v129, v164, |v129|, v125
	v_fma_f32 v130, v164, |v130|, v126
	v_fma_f32 v131, v164, |v131|, v127
	v_mfma_f32_16x16x32_f16 v[124:127], v[116:119], v[24:27], 0
	v_mfma_f32_16x16x32_f16 v[124:127], v[112:115], v[28:31], v[124:127]
	s_nop 1
	v_fma_f32 v128, v166, |v120|, v128
	v_fma_f32 v129, v166, |v121|, v129
	v_fma_f32 v130, v166, |v122|, v130
	v_fma_f32 v131, v166, |v123|, v131
	v_mfma_f32_16x16x32_f16 v[120:123], v[116:119], v[32:35], 0
	v_mfma_f32_16x16x32_f16 v[120:123], v[112:115], v[36:39], v[120:123]
	v_fma_f32 v128, v168, |v124|, v128
	v_fma_f32 v129, v168, |v125|, v129
	v_fma_f32 v130, v168, |v126|, v130
	v_fma_f32 v131, v168, |v127|, v131
	v_mfma_f32_16x16x32_f16 v[124:127], v[116:119], v[40:43], 0
	v_mfma_f32_16x16x32_f16 v[124:127], v[112:115], v[44:47], v[124:127]
	s_nop 1
	v_fma_f32 v128, v170, |v120|, v128
	v_fma_f32 v129, v170, |v121|, v129
; template <int MODE>
; DI void indexer_pass(const _Float16* kbase, int ntile_in, int ts, const f16x8 (&qf)[8][2], const f16x8 (&qc)[2], const float (&wq)[8], float* csc,
;                      unsigned short* cix, int* cnt, float* tau, unsigned* hist, int* oflow, int lane, int w) {
;     ...
;     for (int g = 0; g < NG; ++g) {
;       const int tl = NG * st + g;
;       if (tl < ntile) {
;         f32x4 lin = {0.f, 0.f, 0.f, 0.f};
;         lin = __builtin_amdgcn_mfma_f32_16x16x32_f16(cur[g][0], qc[0], lin, 0, 0, 0);
;         lin = __builtin_amdgcn_mfma_f32_16x16x32_f16(cur[g][1], qc[1], lin, 0, 0, 0);
;         float s[4] = {lin[0], lin[1], lin[2], lin[3]};
;         f32x4 accp = {0.f, 0.f, 0.f, 0.f};
;         accp = __builtin_amdgcn_mfma_f32_16x16x32_f16(cur[g][0], qf[0][0], accp, 0, 0, 0);
;         accp = __builtin_amdgcn_mfma_f32_16x16x32_f16(cur[g][1], qf[0][1], accp, 0, 0, 0);
; #pragma unroll
;         for (int h = 0; h < 8; ++h) {
;           f32x4 accn = {0.f, 0.f, 0.f, 0.f};
;           if (h < 7) {
;             accn = __builtin_amdgcn_mfma_f32_16x16x32_f16(cur[g][0], qf[h + 1][0], accn, 0, 0, 0);
;             accn = __builtin_amdgcn_mfma_f32_16x16x32_f16(cur[g][1], qf[h + 1][1], accn, 0, 0, 0);
;           }
;           __builtin_amdgcn_sched_barrier(0);
; #pragma unroll
;           for (int r = 0; r < 4; ++r) {
;             s[r] = fmaf(wq[h], __builtin_fabsf(accp[r]), s[r]);
;             asm("" : "+v"(s[r]));
;           }
;           __builtin_amdgcn_sched_barrier(0);
;           accp = accn;
;         }
;         if (MODE == 0) {
; #pragma unroll
;           for (int r = 0; r < 4; ++r) {
;             const float score = s[r] + 0.f;
;             const unsigned bits = __float_as_uint(score);
;             int p = (int)((bits & 0x7fffffffu) >> 19) - (HB_LO - 1);
;             p = p < 0 ? 0 : (p > HB_P ? HB_P : p);
;             const int bin = (bits >> 31) ? (HB_P - p) : (HB_P + 1 + p);
;             atomicAdd(hist + q * HB_WORDS + bin, 1u);
;           }
	v_fma_f32 v130, v170, |v122|, v130
	v_fma_f32 v131, v170, |v123|, v131
	v_mfma_f32_16x16x32_f16 v[120:123], v[116:119], v[48:51], 0
	v_mfma_f32_16x16x32_f16 v[120:123], v[112:115], v[52:55], v[120:123]
	v_fma_f32 v124, v172, |v124|, v128
	v_fma_f32 v125, v172, |v125|, v129
	v_fma_f32 v126, v172, |v126|, v130
	v_fma_f32 v127, v172, |v127|, v131
	v_mfma_f32_16x16x32_f16 v[116:119], v[116:119], v[56:59], 0
	v_mfma_f32_16x16x32_f16 v[112:115], v[112:115], v[60:63], v[116:119]
	s_nop 6
	v_fma_f32 v116, v174, |v120|, v124
	v_fma_f32 v118, v174, |v121|, v125
	v_fma_f32 v119, v174, |v122|, v126
	v_fma_f32 v120, v174, |v123|, v127
	s_nop 0
	v_fma_f32 v117, v176, |v112|, v116
	v_fma_f32 v116, v176, |v113|, v118
	v_fma_f32 v113, v176, |v114|, v119
	v_fma_f32 v112, v176, |v115|, v120
	s_nop 0
	v_add_f32_e32 v114, 0, v116
	v_add_f32_e32 v115, 0, v117
	v_add_f32_e32 v112, 0, v112
	v_add_f32_e32 v113, 0, v113
	v_bfe_u32 v116, v115, 19, 12
	v_med3_u32 v116, v116, s76, v203
	v_sub_u32_e32 v117, 0x87f, v116
	v_add_u32_e32 v116, 0xfffff902, v116
	v_cmp_gt_i32_e64 s[0:1], 0, v115
	s_nop 1
	v_cndmask_b32_e64 v115, v116, v117, s[0:1]
	v_lshl_add_u32 v115, v115, 2, v211
	ds_add_u32 v115, v175
	v_bfe_u32 v115, v114, 19, 12
	v_med3_u32 v115, v115, s76, v203
	v_sub_u32_e32 v116, 0x87f, v115
	v_add_u32_e32 v115, 0xfffff902, v115
	v_cmp_gt_i32_e64 s[0:1], 0, v114
	s_nop 1
	v_cndmask_b32_e64 v114, v115, v116, s[0:1]
	v_lshl_add_u32 v114, v114, 2, v211
	ds_add_u32 v114, v175
	v_bfe_u32 v114, v113, 19, 12
	v_med3_u32 v114, v114, s76, v203
	v_sub_u32_e32 v115, 0x87f, v114
	v_add_u32_e32 v114, 0xfffff902, v114
	v_cmp_gt_i32_e64 s[0:1], 0, v113
	s_nop 1
	v_cndmask_b32_e64 v113, v114, v115, s[0:1]
	v_lshl_add_u32 v113, v113, 2, v211
	ds_add_u32 v113, v175
	v_bfe_u32 v113, v112, 19, 12
	v_med3_u32 v113, v113, s76, v203
	v_sub_u32_e32 v114, 0x87f, v113
	v_add_u32_e32 v113, 0xfffff902, v113
	v_cmp_gt_i32_e64 s[0:1], 0, v112
	s_nop 1
	v_cndmask_b32_e64 v112, v113, v114, s[0:1]
	v_lshl_add_u32 v112, v112, 2, v211
	ds_add_u32 v112, v175
.LBB0_279:
	s_or_b64 exec, exec, s[18:19]
	v_cmp_lt_i32_e64 s[0:1], s21, v234
	s_and_saveexec_b64 s[18:19], s[0:1]
	s_cbranch_execz .LBB0_272
	s_waitcnt vmcnt(13)
	v_mfma_f32_16x16x32_f16 v[112:115], v[108:111], v[64:67], 0
	s_waitcnt vmcnt(12)
	v_mfma_f32_16x16x32_f16 v[116:119], v[108:111], v[0:3], 0
	s_waitcnt vmcnt(11)
	v_mfma_f32_16x16x32_f16 v[120:123], v[108:111], v[8:11], 0
	v_mfma_f32_16x16x32_f16 v[112:115], v[104:107], v[68:71], v[112:115]
	v_mfma_f32_16x16x32_f16 v[116:119], v[104:107], v[4:7], v[116:119]
	v_mfma_f32_16x16x32_f16 v[120:123], v[104:107], v[12:15], v[120:123]
	s_nop 6
	v_fma_f32 v116, v162, |v116|, v112
	v_fma_f32 v117, v162, |v117|, v113
	v_fma_f32 v118, v162, |v118|, v114
	v_fma_f32 v119, v162, |v119|, v115
	v_mfma_f32_16x16x32_f16 v[112:115], v[108:111], v[16:19], 0
	v_mfma_f32_16x16x32_f16 v[112:115], v[104:107], v[20:23], v[112:115]
	v_fma_f32 v120, v164, |v120|, v116
	v_fma_f32 v121, v164, |v121|, v117
	v_fma_f32 v122, v164, |v122|, v118
	v_fma_f32 v123, v164, |v123|, v119
	v_mfma_f32_16x16x32_f16 v[116:119], v[108:111], v[24:27], 0
	v_mfma_f32_16x16x32_f16 v[116:119], v[104:107], v[28:31], v[116:119]
	s_nop 1
	v_fma_f32 v120, v166, |v112|, v120
	v_fma_f32 v121, v166, |v113|, v121
	v_fma_f32 v122, v166, |v114|, v122
	v_fma_f32 v123, v166, |v115|, v123
	v_mfma_f32_16x16x32_f16 v[112:115], v[108:111], v[32:35], 0
	v_mfma_f32_16x16x32_f16 v[112:115], v[104:107], v[36:39], v[112:115]
	v_fma_f32 v120, v168, |v116|, v120
	v_fma_f32 v121, v168, |v117|, v121
	v_fma_f32 v122, v168, |v118|, v122
	v_fma_f32 v123, v168, |v119|, v123
	v_mfma_f32_16x16x32_f16 v[116:119], v[108:111], v[40:43], 0
	v_mfma_f32_16x16x32_f16 v[116:119], v[104:107], v[44:47], v[116:119]
	s_nop 1
	v_fma_f32 v120, v170, |v112|, v120
	v_fma_f32 v121, v170, |v113|, v121
	v_fma_f32 v122, v170, |v114|, v122
	v_fma_f32 v123, v170, |v115|, v123
	v_mfma_f32_16x16x32_f16 v[112:115], v[108:111], v[48:51], 0
	v_mfma_f32_16x16x32_f16 v[112:115], v[104:107], v[52:55], v[112:115]
	v_fma_f32 v116, v172, |v116|, v120
	v_fma_f32 v117, v172, |v117|, v121
	v_fma_f32 v118, v172, |v118|, v122
	v_fma_f32 v119, v172, |v119|, v123
	v_mfma_f32_16x16x32_f16 v[108:111], v[108:111], v[56:59], 0
	v_mfma_f32_16x16x32_f16 v[104:107], v[104:107], v[60:63], v[108:111]
	s_nop 6
	v_fma_f32 v108, v174, |v112|, v116
	v_fma_f32 v110, v174, |v113|, v117
	v_fma_f32 v111, v174, |v114|, v118
	v_fma_f32 v112, v174, |v115|, v119
	s_nop 0
	v_fma_f32 v109, v176, |v104|, v108
	v_fma_f32 v108, v176, |v105|, v110
	v_fma_f32 v105, v176, |v106|, v111
	v_fma_f32 v104, v176, |v107|, v112
	s_nop 0
	v_add_f32_e32 v106, 0, v108
	v_add_f32_e32 v107, 0, v109
	v_add_f32_e32 v104, 0, v104
	v_add_f32_e32 v105, 0, v105
	v_bfe_u32 v108, v107, 19, 12
	v_med3_u32 v108, v108, s76, v203
	v_sub_u32_e32 v109, 0x87f, v108
	v_add_u32_e32 v108, 0xfffff902, v108
	v_cmp_gt_i32_e64 s[0:1], 0, v107
	s_nop 1
	v_cndmask_b32_e64 v107, v108, v109, s[0:1]
	v_lshl_add_u32 v107, v107, 2, v211
	ds_add_u32 v107, v175
	v_bfe_u32 v107, v106, 19, 12
	v_med3_u32 v107, v107, s76, v203
	v_sub_u32_e32 v108, 0x87f, v107
	v_add_u32_e32 v107, 0xfffff902, v107
	v_cmp_gt_i32_e64 s[0:1], 0, v106
	s_nop 1
	v_cndmask_b32_e64 v106, v107, v108, s[0:1]
	v_lshl_add_u32 v106, v106, 2, v211
	ds_add_u32 v106, v175
	v_bfe_u32 v106, v105, 19, 12
	v_med3_u32 v106, v106, s76, v203
	v_sub_u32_e32 v107, 0x87f, v106
	v_add_u32_e32 v106, 0xfffff902, v106
	v_cmp_gt_i32_e64 s[0:1], 0, v105
	s_nop 1
	v_cndmask_b32_e64 v105, v106, v107, s[0:1]
	v_lshl_add_u32 v105, v105, 2, v211
	ds_add_u32 v105, v175
	v_bfe_u32 v105, v104, 19, 12
	v_med3_u32 v105, v105, s76, v203
	v_sub_u32_e32 v106, 0x87f, v105
	v_add_u32_e32 v105, 0xfffff902, v105
	v_cmp_gt_i32_e64 s[0:1], 0, v104
	s_nop 1
	v_cndmask_b32_e64 v104, v105, v106, s[0:1]
	v_lshl_add_u32 v104, v104, 2, v211
	ds_add_u32 v104, v175
	s_branch .LBB0_272
